# P0 RMSNorm: 16 of the second-stage row loads hoisted above the first-stage waits (24 rows-loads in flight), waits recounted; plus hand-written decode
# speedup vs baseline: 1.0061x; 1.0049x over previous
.LBB0_66:
	s_andn2_b64 vcc, exec, s[4:5]
	s_cbranch_vccnz .LBB0_69
	s_ashr_i32 s63, s62, 31
	s_lshl_b64 s[2:3], s[62:63], 12
	s_add_u32 s4, s40, s2
	s_addc_u32 s5, s41, s3
	v_lshlrev_b32_e32 v130, 4, v228
	global_load_dwordx4 v[26:29], v130, s[4:5] nt
	global_load_dwordx4 v[22:25], v130, s[4:5] offset:1024 nt
	global_load_dwordx4 v[18:21], v130, s[4:5] offset:2048 nt
	global_load_dwordx4 v[10:13], v130, s[4:5] offset:3072 nt
	v_mov_b32_e32 v131, 0
	s_mov_b32 s2, 0x800000
	v_lshl_add_u64 v[30:31], s[4:5], 0, v[130:131]
	v_add_co_u32_e32 v2, vcc, s2, v30
	s_mov_b64 s[18:19], 0x800000
	s_nop 0
	v_addc_co_u32_e32 v3, vcc, 0, v31, vcc
	global_load_dwordx4 v[106:109], v[2:3], off nt
	v_lshl_add_u64 v[2:3], v[30:31], 0, s[18:19]
	global_load_dwordx4 v[94:97], v[2:3], off offset:1024 nt
	global_load_dwordx4 v[86:89], v[2:3], off offset:2048 nt
	global_load_dwordx4 v[90:93], v[2:3], off offset:3072 nt
	s_mov_b32 s22, 0x1000000
	global_load_dwordx4 v[2:5], v130, s[54:55]
	v_add_co_u32_e32 v46, vcc, s22, v30
	s_mov_b32 s21, 0x1800000
	s_nop 0
	v_addc_co_u32_e32 v47, vcc, 0, v31, vcc
	v_add_co_u32_e32 v44, vcc, s21, v30
	s_brev_b32 s3, 64
	s_nop 0
	v_addc_co_u32_e32 v45, vcc, 0, v31, vcc
	v_add_co_u32_e32 v42, vcc, s3, v30
	s_mov_b32 s20, 0x2800000
	s_nop 0
	v_addc_co_u32_e32 v43, vcc, 0, v31, vcc
	s_mov_b64 s[16:17], 0x2800000
	v_add_co_u32_e32 v38, vcc, s20, v30
	s_mov_b32 s20, 0x358637bd
	v_lshl_add_u64 v[32:33], v[30:31], 0, s[16:17]
	s_mov_b32 s16, 0x3a800000
	v_mov_b64_e32 v[134:135], s[20:21]
	v_addc_co_u32_e32 v39, vcc, 0, v31, vcc
	s_mov_b32 s20, 0x3000000
	s_mov_b32 s23, 0x3800000
	s_mov_b64 s[14:15], 0x1000000
	s_mov_b64 s[12:13], 0x1800000
	s_mov_b64 s[8:9], 0x2000000
	s_mov_b64 s[24:25], 0x3000000
	v_lshl_add_u64 v[40:41], v[30:31], 0, s[14:15]
	v_lshl_add_u64 v[36:37], v[30:31], 0, s[12:13]
	v_lshl_add_u64 v[34:35], v[30:31], 0, s[8:9]
	s_mov_b64 s[26:27], 0x3800000
	v_lshl_add_u64 v[132:133], v[30:31], 0, s[26:27]
	s_lshl_b64 s[10:11], s[62:63], 11
	s_add_u32 s4, s6, s10
	s_addc_u32 s5, s7, s11
	s_cmpk_gt_i32 s62, 0x1ff
	global_load_dwordx4 v[122:125], v[40:41], off offset:1024 nt
	global_load_dwordx4 v[118:121], v[40:41], off offset:2048 nt
	global_load_dwordx4 v[126:129], v[46:47], off nt
	global_load_dwordx4 v[114:117], v[40:41], off offset:3072 nt
	global_load_dwordx4 v[102:105], v[36:37], off offset:1024 nt
	global_load_dwordx4 v[98:101], v[36:37], off offset:2048 nt
	global_load_dwordx4 v[110:113], v[44:45], off nt
	global_load_dwordx4 v[82:85], v[36:37], off offset:3072 nt
	global_load_dwordx4 v[74:77], v[34:35], off offset:1024 nt
	global_load_dwordx4 v[70:73], v[34:35], off offset:2048 nt
	global_load_dwordx4 v[78:81], v[42:43], off nt
	global_load_dwordx4 v[66:69], v[34:35], off offset:3072 nt
	global_load_dwordx4 v[58:61], v[32:33], off offset:1024 nt
	global_load_dwordx4 v[54:57], v[32:33], off offset:2048 nt
	global_load_dwordx4 v[62:65], v[38:39], off nt
	global_load_dwordx4 v[50:53], v[32:33], off offset:3072 nt
	s_waitcnt vmcnt(24)
	v_mul_f32_e32 v1, v27, v27
	v_mul_f32_e32 v6, v29, v29
	s_waitcnt vmcnt(23)
	v_mul_f32_e32 v7, v23, v23
	v_mul_f32_e32 v8, v25, v25
	s_waitcnt vmcnt(22)
	v_mul_f32_e32 v9, v19, v19
	v_mul_f32_e32 v14, v21, v21
	v_fmac_f32_e32 v1, v26, v26
	v_fmac_f32_e32 v6, v28, v28
	v_fmac_f32_e32 v7, v22, v22
	v_fmac_f32_e32 v8, v24, v24
	s_waitcnt vmcnt(21)
	v_mul_f32_e32 v15, v11, v11
	v_mul_f32_e32 v16, v13, v13
	v_fmac_f32_e32 v9, v18, v18
	v_fmac_f32_e32 v14, v20, v20
	v_add_f32_e32 v1, v1, v6
	v_add_f32_e32 v6, v7, v8
	v_fmac_f32_e32 v15, v10, v10
	v_fmac_f32_e32 v16, v12, v12
	v_add_f32_e32 v7, v9, v14
	v_add_f32_e32 v1, v1, v6
	v_add_f32_e32 v8, v15, v16
	v_add_f32_e32 v1, v1, v7
	v_add_f32_e32 v1, v1, v8
	s_waitcnt vmcnt(20)
	v_mul_f32_e32 v9, v107, v107
	v_mul_f32_e32 v14, v109, v109
	v_add_f32_dpp v1, v1, v1 quad_perm:[1,0,3,2] row_mask:0xf bank_mask:0xf bound_ctrl:1
	s_waitcnt vmcnt(19)
	v_mul_f32_e32 v16, v95, v95
	v_fmac_f32_e32 v9, v106, v106
	v_add_f32_dpp v1, v1, v1 quad_perm:[2,3,0,1] row_mask:0xf bank_mask:0xf bound_ctrl:1
	v_fmac_f32_e32 v14, v108, v108
	v_fmac_f32_e32 v16, v94, v94
	v_add_f32_dpp v1, v1, v1 row_half_mirror row_mask:0xf bank_mask:0xf bound_ctrl:1
	v_add_f32_e32 v6, v9, v14
	s_nop 0
	v_add_f32_dpp v1, v1, v1 row_ror:8 row_mask:0xf bank_mask:0xf bound_ctrl:1
	v_mov_b32_e32 v7, v1
	s_nop 1
	v_permlane16_swap_b32_e32 v1, v7
	v_add_f32_e32 v15, v1, v7
	v_mul_f32_e32 v1, v97, v97
	v_fmac_f32_e32 v1, v96, v96
	v_add_f32_e32 v1, v16, v1
	v_add_f32_e32 v1, v6, v1
	s_waitcnt vmcnt(18)
	v_mul_f32_e32 v6, v87, v87
	v_mul_f32_e32 v7, v89, v89
	v_fmac_f32_e32 v6, v86, v86
	v_fmac_f32_e32 v7, v88, v88
	v_add_f32_e32 v6, v6, v7
	v_add_f32_e32 v1, v1, v6
	s_waitcnt vmcnt(17)
	v_mul_f32_e32 v6, v91, v91
	v_mul_f32_e32 v7, v93, v93
	v_fmac_f32_e32 v6, v90, v90
	v_fmac_f32_e32 v7, v92, v92
	v_add_f32_e32 v6, v6, v7
	v_add_f32_e32 v1, v1, v6
	v_mov_b32_e32 v17, v15
	s_nop 1
	v_permlane32_swap_b32_e32 v15, v17
	v_add_f32_dpp v1, v1, v1 quad_perm:[1,0,3,2] row_mask:0xf bank_mask:0xf bound_ctrl:1
	s_nop 1
	v_add_f32_dpp v1, v1, v1 quad_perm:[2,3,0,1] row_mask:0xf bank_mask:0xf bound_ctrl:1
	s_nop 1
	v_add_f32_dpp v1, v1, v1 row_half_mirror row_mask:0xf bank_mask:0xf bound_ctrl:1
	s_nop 1
	v_add_f32_dpp v1, v1, v1 row_ror:8 row_mask:0xf bank_mask:0xf bound_ctrl:1
	v_mov_b32_e32 v6, v1
	s_nop 1
	v_permlane16_swap_b32_e32 v1, v6
	v_add_f32_e32 v14, v1, v6
	v_mov_b32_e32 v16, v14
	s_nop 1
	v_permlane32_swap_b32_e32 v14, v16
	v_pk_add_f32 v[14:15], v[14:15], v[16:17]
	global_load_dwordx4 v[6:9], v130, s[54:55] offset:1024
	v_pk_fma_f32 v[136:137], v[14:15], s[16:17], v[134:135] op_sel_hi:[1,0,0]
	s_movk_i32 s17, 0x7fff
	v_mul_f32_e32 v1, 0x4b800000, v137
	v_cmp_gt_f32_e32 vcc, s2, v137
	s_nop 1
	v_cndmask_b32_e32 v1, v137, v1, vcc
	v_rsq_f32_e32 v1, v1
	s_nop 0
	v_mul_f32_e32 v14, 0x45800000, v1
	v_cndmask_b32_e32 v48, v1, v14, vcc
	global_load_dwordx4 v[14:17], v130, s[54:55] offset:2048
	v_pk_mul_f32 v[146:147], v[10:11], v[48:49] op_sel_hi:[1,0]
	v_pk_mul_f32 v[148:149], v[12:13], v[48:49] op_sel_hi:[1,0]
	global_load_dwordx4 v[10:13], v130, s[54:55] offset:3072
	v_pk_mul_f32 v[26:27], v[26:27], v[48:49] op_sel_hi:[1,0]
	v_pk_mul_f32 v[144:145], v[20:21], v[48:49] op_sel_hi:[1,0]
	s_waitcnt vmcnt(3)
	v_pk_mul_f32 v[20:21], v[2:3], v[26:27]
	v_pk_mul_f32 v[28:29], v[28:29], v[48:49] op_sel_hi:[1,0]
	v_bfe_u32 v1, v20, 16, 1
	v_pk_mul_f32 v[142:143], v[18:19], v[48:49] op_sel_hi:[1,0]
	v_pk_mul_f32 v[18:19], v[4:5], v[28:29]
	v_add3_u32 v1, v20, v1, s17
	v_bfe_u32 v20, v21, 16, 1
	v_add3_u32 v20, v21, v20, s17
	v_bfe_u32 v21, v18, 16, 1
	v_add3_u32 v21, v18, v21, s17
	v_bfe_u32 v18, v19, 16, 1
	v_pk_mul_f32 v[138:139], v[22:23], v[48:49] op_sel_hi:[1,0]
	v_add3_u32 v22, v19, v18, s17
	v_add_co_u32_e32 v18, vcc, s20, v30
	v_lshrrev_b32_e32 v1, 16, v1
	s_nop 0
	v_addc_co_u32_e32 v19, vcc, 0, v31, vcc
	s_mov_b32 s20, 0xffff0000
	v_and_or_b32 v150, v20, s20, v1
	v_lshrrev_b32_e32 v1, 16, v21
	v_add_co_u32_e32 v20, vcc, s23, v30
	v_and_or_b32 v151, v22, s20, v1
	s_nop 0
	v_addc_co_u32_e32 v21, vcc, 0, v31, vcc
	v_lshl_add_u64 v[22:23], v[30:31], 0, s[24:25]
	v_pk_mul_f32 v[140:141], v[24:25], v[48:49] op_sel_hi:[1,0]
	global_load_dwordx4 v[42:45], v[22:23], off offset:1024 nt
	s_nop 0
	global_load_dwordx4 v[38:41], v[22:23], off offset:2048 nt
	global_load_dwordx4 v[46:49], v[18:19], off nt
	global_load_dwordx4 v[34:37], v[22:23], off offset:3072 nt
	global_load_dwordx4 v[26:29], v[132:133], off offset:1024 nt
	s_nop 0
	global_load_dwordx4 v[22:25], v[132:133], off offset:2048 nt
	global_load_dwordx4 v[30:33], v[20:21], off nt
	s_nop 0
	global_load_dwordx4 v[18:21], v[132:133], off offset:3072 nt
	v_lshlrev_b32_e32 v132, 3, v228
	global_store_dwordx2 v132, v[150:151], s[4:5] sc1
	v_cmp_gt_f32_e32 vcc, s2, v136
	s_mov_b32 s23, 0x400000
	s_waitcnt vmcnt(11)
	v_pk_mul_f32 v[138:139], v[6:7], v[138:139]
	s_nop 0
	v_bfe_u32 v1, v138, 16, 1
	v_bfe_u32 v133, v139, 16, 1
	v_add3_u32 v1, v138, v1, s17
	v_add3_u32 v133, v139, v133, s17
	v_pk_mul_f32 v[138:139], v[8:9], v[140:141]
	v_lshrrev_b32_e32 v1, 16, v1
	v_bfe_u32 v137, v138, 16, 1
	v_add3_u32 v137, v138, v137, s17
	v_bfe_u32 v138, v139, 16, 1
	v_add3_u32 v139, v139, v138, s17
	v_and_or_b32 v138, v133, s20, v1
	v_lshrrev_b32_e32 v1, 16, v137
	v_and_or_b32 v139, v139, s20, v1
	global_store_dwordx2 v132, v[138:139], s[4:5] offset:512 sc1
	s_waitcnt vmcnt(11)
	v_pk_mul_f32 v[138:139], v[14:15], v[142:143]
	s_nop 0
	v_bfe_u32 v1, v138, 16, 1
	v_bfe_u32 v133, v139, 16, 1
	v_add3_u32 v1, v138, v1, s17
	v_add3_u32 v133, v139, v133, s17
	v_pk_mul_f32 v[138:139], v[16:17], v[144:145]
	v_lshrrev_b32_e32 v1, 16, v1
	v_bfe_u32 v137, v138, 16, 1
	v_add3_u32 v137, v138, v137, s17
	v_bfe_u32 v138, v139, 16, 1
	v_add3_u32 v139, v139, v138, s17
	v_and_or_b32 v138, v133, s20, v1
	v_lshrrev_b32_e32 v1, 16, v137
	v_and_or_b32 v139, v139, s20, v1
	global_store_dwordx2 v132, v[138:139], s[4:5] offset:1024 sc1
	s_waitcnt vmcnt(11)
	v_pk_mul_f32 v[138:139], v[10:11], v[146:147]
	s_nop 0
	v_bfe_u32 v1, v138, 16, 1
	v_bfe_u32 v133, v139, 16, 1
	v_add3_u32 v1, v138, v1, s17
	v_add3_u32 v133, v139, v133, s17
	v_pk_mul_f32 v[138:139], v[12:13], v[148:149]
	v_lshrrev_b32_e32 v1, 16, v1
	v_bfe_u32 v137, v138, 16, 1
	v_add3_u32 v137, v138, v137, s17
	v_bfe_u32 v138, v139, 16, 1
	v_add3_u32 v139, v139, v138, s17
	v_and_or_b32 v138, v133, s20, v1
	v_mul_f32_e32 v1, 0x4b800000, v136
	v_cndmask_b32_e32 v1, v136, v1, vcc
	v_rsq_f32_e32 v1, v1
	v_lshrrev_b32_e32 v133, 16, v137
	v_and_or_b32 v139, v139, s20, v133
	global_store_dwordx2 v132, v[138:139], s[4:5] offset:1536 sc1
	v_mul_f32_e32 v133, 0x45800000, v1
	v_cndmask_b32_e32 v136, v1, v133, vcc
	v_pk_mul_f32 v[106:107], v[106:107], v[136:137] op_sel_hi:[1,0]
	v_pk_mul_f32 v[108:109], v[108:109], v[136:137] op_sel_hi:[1,0]
	v_pk_mul_f32 v[106:107], v[2:3], v[106:107]
	v_pk_mul_f32 v[94:95], v[94:95], v[136:137] op_sel_hi:[1,0]
	v_bfe_u32 v1, v106, 16, 1
	v_add3_u32 v1, v106, v1, s17
	v_bfe_u32 v106, v107, 16, 1
	v_add3_u32 v133, v107, v106, s17
	v_pk_mul_f32 v[106:107], v[4:5], v[108:109]
	v_lshrrev_b32_e32 v1, 16, v1
	v_bfe_u32 v108, v106, 16, 1
	v_add3_u32 v106, v106, v108, s17
	v_bfe_u32 v108, v107, 16, 1
	v_add3_u32 v107, v107, v108, s17
	v_and_or_b32 v108, v133, s20, v1
	v_lshrrev_b32_e32 v1, 16, v106
	v_mov_b32_e32 v133, v131
	v_and_or_b32 v109, v107, s20, v1
	v_lshl_add_u64 v[106:107], s[4:5], 0, v[132:133]
	v_pk_mul_f32 v[94:95], v[6:7], v[94:95]
	v_add_co_u32_e32 v138, vcc, s23, v106
	v_bfe_u32 v1, v94, 16, 1
	s_nop 0
	v_addc_co_u32_e32 v139, vcc, 0, v107, vcc
	v_pk_mul_f32 v[96:97], v[96:97], v[136:137] op_sel_hi:[1,0]
	v_add3_u32 v1, v94, v1, s17
	v_bfe_u32 v94, v95, 16, 1
	global_store_dwordx2 v[138:139], v[108:109], off sc1
	v_add3_u32 v108, v95, v94, s17
	v_pk_mul_f32 v[94:95], v[8:9], v[96:97]
	v_pk_mul_f32 v[86:87], v[86:87], v[136:137] op_sel_hi:[1,0]
	v_bfe_u32 v96, v94, 16, 1
	v_add3_u32 v96, v94, v96, s17
	v_bfe_u32 v94, v95, 16, 1
	v_lshrrev_b32_e32 v1, 16, v1
	v_add3_u32 v95, v95, v94, s17
	v_and_or_b32 v94, v108, s20, v1
	v_lshrrev_b32_e32 v1, 16, v96
	v_pk_mul_f32 v[86:87], v[14:15], v[86:87]
	v_and_or_b32 v95, v95, s20, v1
	s_mov_b64 s[4:5], 0x400000
	v_bfe_u32 v1, v86, 16, 1
	v_pk_mul_f32 v[88:89], v[88:89], v[136:137] op_sel_hi:[1,0]
	v_lshl_add_u64 v[96:97], v[106:107], 0, s[4:5]
	v_add3_u32 v1, v86, v1, s17
	v_bfe_u32 v86, v87, 16, 1
	global_store_dwordx2 v[96:97], v[94:95], off offset:512 sc1
	v_add3_u32 v94, v87, v86, s17
	v_pk_mul_f32 v[86:87], v[16:17], v[88:89]
	v_lshrrev_b32_e32 v1, 16, v1
	v_bfe_u32 v88, v86, 16, 1
	v_add3_u32 v88, v86, v88, s17
	v_bfe_u32 v86, v87, 16, 1
	v_add3_u32 v87, v87, v86, s17
	v_and_or_b32 v86, v94, s20, v1
	v_lshrrev_b32_e32 v1, 16, v88
	v_pk_mul_f32 v[90:91], v[90:91], v[136:137] op_sel_hi:[1,0]
	v_and_or_b32 v87, v87, s20, v1
	global_store_dwordx2 v[96:97], v[86:87], off offset:1024 sc1
	v_pk_mul_f32 v[86:87], v[10:11], v[90:91]
	v_pk_mul_f32 v[92:93], v[92:93], v[136:137] op_sel_hi:[1,0]
	v_bfe_u32 v1, v86, 16, 1
	v_add3_u32 v1, v86, v1, s17
	v_bfe_u32 v86, v87, 16, 1
	v_add3_u32 v88, v87, v86, s17
	v_pk_mul_f32 v[86:87], v[12:13], v[92:93]
	v_lshrrev_b32_e32 v1, 16, v1
	v_bfe_u32 v89, v86, 16, 1
	v_add3_u32 v92, v86, v89, s17
	v_bfe_u32 v86, v87, 16, 1
	v_add3_u32 v87, v87, v86, s17
	v_and_or_b32 v86, v88, s20, v1
	s_waitcnt vmcnt(28)
	v_mul_f32_e32 v1, v127, v127
	v_mul_f32_e32 v88, v129, v129
	v_fmac_f32_e32 v1, v126, v126
	v_fmac_f32_e32 v88, v128, v128
	v_add_f32_e32 v1, v1, v88
	v_mul_f32_e32 v88, v123, v123
	v_mul_f32_e32 v89, v125, v125
	v_fmac_f32_e32 v88, v122, v122
	v_fmac_f32_e32 v89, v124, v124
	v_add_f32_e32 v88, v88, v89
	v_add_f32_e32 v1, v1, v88
	v_mul_f32_e32 v88, v119, v119
	v_mul_f32_e32 v89, v121, v121
	v_fmac_f32_e32 v88, v118, v118
	v_fmac_f32_e32 v89, v120, v120
	v_add_f32_e32 v88, v88, v89
	v_add_f32_e32 v1, v1, v88
	s_waitcnt vmcnt(27)
	v_mul_f32_e32 v88, v115, v115
	v_mul_f32_e32 v89, v117, v117
	v_fmac_f32_e32 v88, v114, v114
	v_fmac_f32_e32 v89, v116, v116
	v_add_f32_e32 v88, v88, v89
	v_add_f32_e32 v1, v1, v88
	s_waitcnt vmcnt(24)
	v_mul_f32_e32 v88, v111, v111
	v_mul_f32_e32 v89, v113, v113
	v_fmac_f32_e32 v88, v110, v110
	v_fmac_f32_e32 v89, v112, v112
	v_add_f32_e32 v88, v88, v89
	v_mul_f32_e32 v89, v103, v103
	v_mul_f32_e32 v90, v105, v105
	v_fmac_f32_e32 v89, v102, v102
	v_fmac_f32_e32 v90, v104, v104
	v_add_f32_e32 v89, v89, v90
	v_add_f32_e32 v88, v88, v89
	v_mul_f32_e32 v89, v99, v99
	v_mul_f32_e32 v90, v101, v101
	v_fmac_f32_e32 v89, v98, v98
	v_fmac_f32_e32 v90, v100, v100
	v_add_f32_e32 v89, v89, v90
	v_add_f32_dpp v1, v1, v1 quad_perm:[1,0,3,2] row_mask:0xf bank_mask:0xf bound_ctrl:1
	v_add_f32_e32 v88, v88, v89
	s_waitcnt vmcnt(23)
	v_mul_f32_e32 v89, v83, v83
	v_mul_f32_e32 v90, v85, v85
	v_add_f32_dpp v1, v1, v1 quad_perm:[2,3,0,1] row_mask:0xf bank_mask:0xf bound_ctrl:1
	v_fmac_f32_e32 v89, v82, v82
	v_fmac_f32_e32 v90, v84, v84
	v_add_f32_dpp v1, v1, v1 row_half_mirror row_mask:0xf bank_mask:0xf bound_ctrl:1
	v_add_f32_e32 v89, v89, v90
	v_add_f32_e32 v88, v88, v89
	v_add_f32_dpp v1, v1, v1 row_ror:8 row_mask:0xf bank_mask:0xf bound_ctrl:1
	v_mov_b32_e32 v89, v1
	s_nop 1
	v_permlane16_swap_b32_e32 v1, v89
	v_add_f32_e32 v89, v1, v89
	s_nop 0
	v_add_f32_dpp v1, v88, v88 quad_perm:[1,0,3,2] row_mask:0xf bank_mask:0xf bound_ctrl:1
	v_mov_b32_e32 v91, v89
	s_nop 1
	v_permlane32_swap_b32_e32 v89, v91
	v_add_f32_dpp v1, v1, v1 quad_perm:[2,3,0,1] row_mask:0xf bank_mask:0xf bound_ctrl:1
	s_mov_b32 s4, 0xc00000
	s_nop 0
	v_add_f32_dpp v1, v1, v1 row_half_mirror row_mask:0xf bank_mask:0xf bound_ctrl:1
	s_nop 1
	v_add_f32_dpp v1, v1, v1 row_ror:8 row_mask:0xf bank_mask:0xf bound_ctrl:1
	v_mov_b32_e32 v88, v1
	s_nop 1
	v_permlane16_swap_b32_e32 v1, v88
	v_add_f32_e32 v88, v1, v88
	v_mov_b32_e32 v90, v88
	s_nop 1
	v_permlane32_swap_b32_e32 v88, v90
	v_pk_add_f32 v[88:89], v[88:89], v[90:91]
	s_nop 0
	v_pk_fma_f32 v[88:89], v[88:89], s[16:17], v[134:135] op_sel_hi:[1,0,0]
	s_nop 0
	v_mul_f32_e32 v1, 0x4b800000, v89
	v_cmp_gt_f32_e32 vcc, s2, v89
	s_nop 1
	v_cndmask_b32_e32 v1, v89, v1, vcc
	v_rsq_f32_e32 v1, v1
	v_lshrrev_b32_e32 v89, 16, v92
	v_and_or_b32 v87, v87, s20, v89
	global_store_dwordx2 v[96:97], v[86:87], off offset:1536 sc1
	v_mul_f32_e32 v86, 0x45800000, v1
	v_cndmask_b32_e32 v86, v1, v86, vcc
	v_pk_mul_f32 v[90:91], v[126:127], v[86:87] op_sel_hi:[1,0]
	v_pk_mul_f32 v[92:93], v[128:129], v[86:87] op_sel_hi:[1,0]
	v_pk_mul_f32 v[90:91], v[2:3], v[90:91]
	s_nop 0
	v_bfe_u32 v1, v90, 16, 1
	v_bfe_u32 v87, v91, 16, 1
	v_add3_u32 v1, v90, v1, s17
	v_add3_u32 v87, v91, v87, s17
	v_pk_mul_f32 v[90:91], v[4:5], v[92:93]
	v_lshrrev_b32_e32 v1, 16, v1
	v_bfe_u32 v89, v90, 16, 1
	v_add3_u32 v89, v90, v89, s17
	v_bfe_u32 v90, v91, 16, 1
	v_add3_u32 v91, v91, v90, s17
	v_and_or_b32 v90, v87, s20, v1
	v_lshrrev_b32_e32 v1, 16, v89
	v_add_co_u32_e32 v92, vcc, s2, v106
	v_and_or_b32 v91, v91, s20, v1
	s_nop 0
	v_addc_co_u32_e32 v93, vcc, 0, v107, vcc
	global_store_dwordx2 v[92:93], v[90:91], off sc1
	v_pk_mul_f32 v[90:91], v[122:123], v[86:87] op_sel_hi:[1,0]
	v_pk_mul_f32 v[92:93], v[124:125], v[86:87] op_sel_hi:[1,0]
	v_pk_mul_f32 v[90:91], v[6:7], v[90:91]
	v_pk_mul_f32 v[94:95], v[118:119], v[86:87] op_sel_hi:[1,0]
	v_bfe_u32 v1, v90, 16, 1
	v_bfe_u32 v89, v91, 16, 1
	v_add3_u32 v1, v90, v1, s17
	v_add3_u32 v89, v91, v89, s17
	v_pk_mul_f32 v[90:91], v[8:9], v[92:93]
	v_lshrrev_b32_e32 v1, 16, v1
	v_bfe_u32 v92, v90, 16, 1
	v_add3_u32 v92, v90, v92, s17
	v_bfe_u32 v90, v91, 16, 1
	v_add3_u32 v91, v91, v90, s17
	v_and_or_b32 v90, v89, s20, v1
	v_lshrrev_b32_e32 v1, 16, v92
	v_and_or_b32 v91, v91, s20, v1
	v_lshl_add_u64 v[92:93], v[106:107], 0, s[18:19]
	global_store_dwordx2 v[92:93], v[90:91], off offset:512 sc1
	v_pk_mul_f32 v[90:91], v[14:15], v[94:95]
	v_pk_mul_f32 v[96:97], v[120:121], v[86:87] op_sel_hi:[1,0]
	v_bfe_u32 v1, v90, 16, 1
	v_bfe_u32 v89, v91, 16, 1
	v_add3_u32 v1, v90, v1, s17
	v_add3_u32 v89, v91, v89, s17
	v_pk_mul_f32 v[90:91], v[16:17], v[96:97]
	v_lshrrev_b32_e32 v1, 16, v1
	v_bfe_u32 v94, v90, 16, 1
	v_add3_u32 v94, v90, v94, s17
	v_bfe_u32 v90, v91, 16, 1
	v_add3_u32 v91, v91, v90, s17
	v_and_or_b32 v90, v89, s20, v1
	v_lshrrev_b32_e32 v1, 16, v94
	v_pk_mul_f32 v[108:109], v[114:115], v[86:87] op_sel_hi:[1,0]
	v_and_or_b32 v91, v91, s20, v1
	v_pk_mul_f32 v[86:87], v[116:117], v[86:87] op_sel_hi:[1,0]
	global_store_dwordx2 v[92:93], v[90:91], off offset:1024 sc1
	v_pk_mul_f32 v[90:91], v[10:11], v[108:109]
	v_pk_mul_f32 v[86:87], v[12:13], v[86:87]
	v_bfe_u32 v1, v90, 16, 1
	v_add3_u32 v1, v90, v1, s17
	v_bfe_u32 v89, v91, 16, 1
	v_bfe_u32 v90, v86, 16, 1
	v_add3_u32 v89, v91, v89, s17
	v_add3_u32 v90, v86, v90, s17
	v_bfe_u32 v86, v87, 16, 1
	v_lshrrev_b32_e32 v1, 16, v1
	v_add3_u32 v87, v87, v86, s17
	v_and_or_b32 v86, v89, s20, v1
	v_mul_f32_e32 v1, 0x4b800000, v88
	v_cmp_gt_f32_e32 vcc, s2, v88
	s_nop 1
	v_cndmask_b32_e32 v1, v88, v1, vcc
	v_rsq_f32_e32 v1, v1
	v_lshrrev_b32_e32 v88, 16, v90
	v_and_or_b32 v87, v87, s20, v88
	global_store_dwordx2 v[92:93], v[86:87], off offset:1536 sc1
	v_mul_f32_e32 v86, 0x45800000, v1
	v_cndmask_b32_e32 v86, v1, v86, vcc
	v_pk_mul_f32 v[88:89], v[110:111], v[86:87] op_sel_hi:[1,0]
	v_pk_mul_f32 v[90:91], v[112:113], v[86:87] op_sel_hi:[1,0]
	v_pk_mul_f32 v[88:89], v[2:3], v[88:89]
	s_nop 0
	v_bfe_u32 v1, v88, 16, 1
	v_bfe_u32 v87, v89, 16, 1
	v_add3_u32 v1, v88, v1, s17
	v_add3_u32 v87, v89, v87, s17
	v_pk_mul_f32 v[88:89], v[4:5], v[90:91]
	v_lshrrev_b32_e32 v1, 16, v1
	v_bfe_u32 v90, v88, 16, 1
	v_add3_u32 v90, v88, v90, s17
	v_bfe_u32 v88, v89, 16, 1
	v_add3_u32 v89, v89, v88, s17
	v_and_or_b32 v88, v87, s20, v1
	v_lshrrev_b32_e32 v1, 16, v90
	v_add_co_u32_e32 v90, vcc, s4, v106
	v_and_or_b32 v89, v89, s20, v1
	s_nop 0
	v_addc_co_u32_e32 v91, vcc, 0, v107, vcc
	global_store_dwordx2 v[90:91], v[88:89], off sc1
	v_pk_mul_f32 v[88:89], v[102:103], v[86:87] op_sel_hi:[1,0]
	v_pk_mul_f32 v[90:91], v[104:105], v[86:87] op_sel_hi:[1,0]
	v_pk_mul_f32 v[92:93], v[98:99], v[86:87] op_sel_hi:[1,0]
	v_pk_mul_f32 v[94:95], v[100:101], v[86:87] op_sel_hi:[1,0]
	v_pk_mul_f32 v[82:83], v[82:83], v[86:87] op_sel_hi:[1,0]
	v_pk_mul_f32 v[84:85], v[84:85], v[86:87] op_sel_hi:[1,0]
	v_pk_mul_f32 v[86:87], v[6:7], v[88:89]
	s_mov_b64 s[4:5], 0xc00000
	v_bfe_u32 v1, v86, 16, 1
	v_add3_u32 v1, v86, v1, s17
	v_bfe_u32 v86, v87, 16, 1
	v_add3_u32 v88, v87, v86, s17
	v_pk_mul_f32 v[86:87], v[8:9], v[90:91]
	v_lshrrev_b32_e32 v1, 16, v1
	v_bfe_u32 v89, v86, 16, 1
	v_add3_u32 v89, v86, v89, s17
	v_bfe_u32 v86, v87, 16, 1
	v_add3_u32 v87, v87, v86, s17
	v_and_or_b32 v86, v88, s20, v1
	v_lshrrev_b32_e32 v1, 16, v89
	v_and_or_b32 v87, v87, s20, v1
	v_lshl_add_u64 v[88:89], v[106:107], 0, s[4:5]
	global_store_dwordx2 v[88:89], v[86:87], off offset:512 sc1
	v_pk_mul_f32 v[86:87], v[14:15], v[92:93]
	v_pk_mul_f32 v[82:83], v[10:11], v[82:83]
	v_bfe_u32 v1, v86, 16, 1
	v_add3_u32 v1, v86, v1, s17
	v_bfe_u32 v86, v87, 16, 1
	v_add3_u32 v90, v87, v86, s17
	v_pk_mul_f32 v[86:87], v[16:17], v[94:95]
	v_lshrrev_b32_e32 v1, 16, v1
	v_bfe_u32 v91, v86, 16, 1
	v_add3_u32 v91, v86, v91, s17
	v_bfe_u32 v86, v87, 16, 1
	v_add3_u32 v87, v87, v86, s17
	v_and_or_b32 v86, v90, s20, v1
	v_lshrrev_b32_e32 v1, 16, v91
	v_and_or_b32 v87, v87, s20, v1
	v_bfe_u32 v1, v82, 16, 1
	v_add3_u32 v1, v82, v1, s17
	v_bfe_u32 v82, v83, 16, 1
	global_store_dwordx2 v[88:89], v[86:87], off offset:1024 sc1
	v_add3_u32 v86, v83, v82, s17
	v_pk_mul_f32 v[82:83], v[12:13], v[84:85]
	v_lshrrev_b32_e32 v1, 16, v1
	v_bfe_u32 v84, v82, 16, 1
	v_add3_u32 v90, v82, v84, s17
	v_bfe_u32 v82, v83, 16, 1
	v_add3_u32 v83, v83, v82, s17
	v_and_or_b32 v82, v86, s20, v1
	s_waitcnt vmcnt(28)
	v_mul_f32_e32 v1, v79, v79
	v_mul_f32_e32 v84, v81, v81
	v_fmac_f32_e32 v1, v78, v78
	v_fmac_f32_e32 v84, v80, v80
	v_add_f32_e32 v1, v1, v84
	v_mul_f32_e32 v84, v75, v75
	v_mul_f32_e32 v85, v77, v77
	v_fmac_f32_e32 v84, v74, v74
	v_fmac_f32_e32 v85, v76, v76
	v_add_f32_e32 v84, v84, v85
	v_add_f32_e32 v1, v1, v84
	v_mul_f32_e32 v84, v71, v71
	v_mul_f32_e32 v85, v73, v73
	v_fmac_f32_e32 v84, v70, v70
	v_fmac_f32_e32 v85, v72, v72
	v_add_f32_e32 v84, v84, v85
	v_add_f32_e32 v1, v1, v84
	s_waitcnt vmcnt(27)
	v_mul_f32_e32 v84, v67, v67
	v_mul_f32_e32 v85, v69, v69
	v_fmac_f32_e32 v84, v66, v66
	v_fmac_f32_e32 v85, v68, v68
	v_add_f32_e32 v84, v84, v85
	v_add_f32_e32 v1, v1, v84
	s_waitcnt vmcnt(24)
	v_mul_f32_e32 v84, v63, v63
	v_mul_f32_e32 v85, v65, v65
	v_fmac_f32_e32 v84, v62, v62
	v_fmac_f32_e32 v85, v64, v64
	v_add_f32_e32 v84, v84, v85
	v_mul_f32_e32 v85, v59, v59
	v_mul_f32_e32 v86, v61, v61
	v_fmac_f32_e32 v85, v58, v58
	v_fmac_f32_e32 v86, v60, v60
	v_add_f32_e32 v85, v85, v86
	v_add_f32_e32 v84, v84, v85
	v_mul_f32_e32 v85, v55, v55
	v_mul_f32_e32 v86, v57, v57
	v_fmac_f32_e32 v85, v54, v54
	v_fmac_f32_e32 v86, v56, v56
	v_add_f32_e32 v85, v85, v86
	v_add_f32_dpp v1, v1, v1 quad_perm:[1,0,3,2] row_mask:0xf bank_mask:0xf bound_ctrl:1
	v_add_f32_e32 v84, v84, v85
	s_waitcnt vmcnt(23)
	v_mul_f32_e32 v85, v51, v51
	v_mul_f32_e32 v86, v53, v53
	v_add_f32_dpp v1, v1, v1 quad_perm:[2,3,0,1] row_mask:0xf bank_mask:0xf bound_ctrl:1
	v_fmac_f32_e32 v85, v50, v50
	v_fmac_f32_e32 v86, v52, v52
	v_add_f32_dpp v1, v1, v1 row_half_mirror row_mask:0xf bank_mask:0xf bound_ctrl:1
	v_add_f32_e32 v85, v85, v86
	v_add_f32_e32 v84, v84, v85
	v_add_f32_dpp v1, v1, v1 row_ror:8 row_mask:0xf bank_mask:0xf bound_ctrl:1
	v_mov_b32_e32 v85, v1
	s_nop 1
	v_permlane16_swap_b32_e32 v1, v85
	v_add_f32_e32 v85, v1, v85
	s_nop 0
	v_add_f32_dpp v1, v84, v84 quad_perm:[1,0,3,2] row_mask:0xf bank_mask:0xf bound_ctrl:1
	v_mov_b32_e32 v87, v85
	s_nop 1
	v_permlane32_swap_b32_e32 v85, v87
	v_add_f32_dpp v1, v1, v1 quad_perm:[2,3,0,1] row_mask:0xf bank_mask:0xf bound_ctrl:1
	s_mov_b32 s4, 0x1400000
	s_nop 0
	v_add_f32_dpp v1, v1, v1 row_half_mirror row_mask:0xf bank_mask:0xf bound_ctrl:1
	s_nop 1
	v_add_f32_dpp v1, v1, v1 row_ror:8 row_mask:0xf bank_mask:0xf bound_ctrl:1
	v_mov_b32_e32 v84, v1
	s_nop 1
	v_permlane16_swap_b32_e32 v1, v84
	v_add_f32_e32 v84, v1, v84
	v_mov_b32_e32 v86, v84
	s_nop 1
	v_permlane32_swap_b32_e32 v84, v86
	v_pk_add_f32 v[84:85], v[84:85], v[86:87]
	s_nop 0
	v_pk_fma_f32 v[84:85], v[84:85], s[16:17], v[134:135] op_sel_hi:[1,0,0]
	s_nop 0
	v_mul_f32_e32 v1, 0x4b800000, v85
	v_cmp_gt_f32_e32 vcc, s2, v85
	s_nop 1
	v_cndmask_b32_e32 v1, v85, v1, vcc
	v_rsq_f32_e32 v1, v1
	v_lshrrev_b32_e32 v85, 16, v90
	v_and_or_b32 v83, v83, s20, v85
	global_store_dwordx2 v[88:89], v[82:83], off offset:1536 sc1
	v_mul_f32_e32 v82, 0x45800000, v1
	v_cndmask_b32_e32 v82, v1, v82, vcc
	v_pk_mul_f32 v[78:79], v[78:79], v[82:83] op_sel_hi:[1,0]
	v_pk_mul_f32 v[80:81], v[80:81], v[82:83] op_sel_hi:[1,0]
	v_pk_mul_f32 v[78:79], v[2:3], v[78:79]
	s_nop 0
	v_bfe_u32 v1, v78, 16, 1
	v_add3_u32 v1, v78, v1, s17
	v_bfe_u32 v78, v79, 16, 1
	v_add3_u32 v83, v79, v78, s17
	v_pk_mul_f32 v[78:79], v[4:5], v[80:81]
	v_lshrrev_b32_e32 v1, 16, v1
	v_bfe_u32 v80, v78, 16, 1
	v_add3_u32 v80, v78, v80, s17
	v_bfe_u32 v78, v79, 16, 1
	v_pk_mul_f32 v[74:75], v[74:75], v[82:83] op_sel_hi:[1,0]
	v_add3_u32 v79, v79, v78, s17
	v_and_or_b32 v78, v83, s20, v1
	v_lshrrev_b32_e32 v1, 16, v80
	v_pk_mul_f32 v[74:75], v[6:7], v[74:75]
	v_and_or_b32 v79, v79, s20, v1
	v_add_co_u32_e32 v80, vcc, s22, v106
	v_bfe_u32 v1, v74, 16, 1
	s_nop 0
	v_addc_co_u32_e32 v81, vcc, 0, v107, vcc
	v_pk_mul_f32 v[76:77], v[76:77], v[82:83] op_sel_hi:[1,0]
	v_add3_u32 v1, v74, v1, s17
	v_bfe_u32 v74, v75, 16, 1
	global_store_dwordx2 v[80:81], v[78:79], off sc1
	v_add3_u32 v78, v75, v74, s17
	v_pk_mul_f32 v[74:75], v[8:9], v[76:77]
	v_pk_mul_f32 v[70:71], v[70:71], v[82:83] op_sel_hi:[1,0]
	v_bfe_u32 v76, v74, 16, 1
	v_add3_u32 v76, v74, v76, s17
	v_bfe_u32 v74, v75, 16, 1
	v_lshrrev_b32_e32 v1, 16, v1
	v_add3_u32 v75, v75, v74, s17
	v_and_or_b32 v74, v78, s20, v1
	v_lshrrev_b32_e32 v1, 16, v76
	v_pk_mul_f32 v[70:71], v[14:15], v[70:71]
	v_and_or_b32 v75, v75, s20, v1
	v_bfe_u32 v1, v70, 16, 1
	v_pk_mul_f32 v[72:73], v[72:73], v[82:83] op_sel_hi:[1,0]
	v_lshl_add_u64 v[76:77], v[106:107], 0, s[14:15]
	v_add3_u32 v1, v70, v1, s17
	v_bfe_u32 v70, v71, 16, 1
	global_store_dwordx2 v[76:77], v[74:75], off offset:512 sc1
	v_add3_u32 v74, v71, v70, s17
	v_pk_mul_f32 v[70:71], v[16:17], v[72:73]
	v_pk_mul_f32 v[66:67], v[66:67], v[82:83] op_sel_hi:[1,0]
	v_bfe_u32 v72, v70, 16, 1
	v_add3_u32 v72, v70, v72, s17
	v_bfe_u32 v70, v71, 16, 1
	v_lshrrev_b32_e32 v1, 16, v1
	v_add3_u32 v71, v71, v70, s17
	v_and_or_b32 v70, v74, s20, v1
	v_lshrrev_b32_e32 v1, 16, v72
	v_pk_mul_f32 v[66:67], v[10:11], v[66:67]
	v_and_or_b32 v71, v71, s20, v1
	v_bfe_u32 v1, v66, 16, 1
	v_pk_mul_f32 v[68:69], v[68:69], v[82:83] op_sel_hi:[1,0]
	v_add3_u32 v1, v66, v1, s17
	v_bfe_u32 v66, v67, 16, 1
	global_store_dwordx2 v[76:77], v[70:71], off offset:1024 sc1
	v_add3_u32 v70, v67, v66, s17
	v_pk_mul_f32 v[66:67], v[12:13], v[68:69]
	v_lshrrev_b32_e32 v1, 16, v1
	v_bfe_u32 v68, v66, 16, 1
	v_add3_u32 v68, v66, v68, s17
	v_bfe_u32 v66, v67, 16, 1
	v_add3_u32 v67, v67, v66, s17
	v_and_or_b32 v66, v70, s20, v1
	v_mul_f32_e32 v1, 0x4b800000, v84
	v_cmp_gt_f32_e32 vcc, s2, v84
	v_lshrrev_b32_e32 v68, 16, v68
	v_and_or_b32 v67, v67, s20, v68
	v_cndmask_b32_e32 v1, v84, v1, vcc
	v_rsq_f32_e32 v1, v1
	global_store_dwordx2 v[76:77], v[66:67], off offset:1536 sc1
	v_mul_f32_e32 v66, 0x45800000, v1
	v_cndmask_b32_e32 v66, v1, v66, vcc
	v_pk_mul_f32 v[62:63], v[62:63], v[66:67] op_sel_hi:[1,0]
	v_pk_mul_f32 v[64:65], v[64:65], v[66:67] op_sel_hi:[1,0]
	v_pk_mul_f32 v[62:63], v[2:3], v[62:63]
	s_nop 0
	v_bfe_u32 v1, v62, 16, 1
	v_add3_u32 v1, v62, v1, s17
	v_bfe_u32 v62, v63, 16, 1
	v_add3_u32 v67, v63, v62, s17
	v_pk_mul_f32 v[62:63], v[4:5], v[64:65]
	v_lshrrev_b32_e32 v1, 16, v1
	v_bfe_u32 v64, v62, 16, 1
	v_add3_u32 v64, v62, v64, s17
	v_bfe_u32 v62, v63, 16, 1
	v_pk_mul_f32 v[58:59], v[58:59], v[66:67] op_sel_hi:[1,0]
	v_add3_u32 v63, v63, v62, s17
	v_and_or_b32 v62, v67, s20, v1
	v_lshrrev_b32_e32 v1, 16, v64
	v_pk_mul_f32 v[58:59], v[6:7], v[58:59]
	v_and_or_b32 v63, v63, s20, v1
	v_add_co_u32_e32 v64, vcc, s4, v106
	v_bfe_u32 v1, v58, 16, 1
	s_nop 0
	v_addc_co_u32_e32 v65, vcc, 0, v107, vcc
	v_pk_mul_f32 v[60:61], v[60:61], v[66:67] op_sel_hi:[1,0]
	v_add3_u32 v1, v58, v1, s17
	v_bfe_u32 v58, v59, 16, 1
	global_store_dwordx2 v[64:65], v[62:63], off sc1
	v_add3_u32 v62, v59, v58, s17
	v_pk_mul_f32 v[58:59], v[8:9], v[60:61]
	v_lshrrev_b32_e32 v1, 16, v1
	v_bfe_u32 v60, v58, 16, 1
	v_add3_u32 v60, v58, v60, s17
	v_bfe_u32 v58, v59, 16, 1
	v_pk_mul_f32 v[54:55], v[54:55], v[66:67] op_sel_hi:[1,0]
	v_add3_u32 v59, v59, v58, s17
	v_and_or_b32 v58, v62, s20, v1
	v_lshrrev_b32_e32 v1, 16, v60
	v_pk_mul_f32 v[54:55], v[14:15], v[54:55]
	v_and_or_b32 v59, v59, s20, v1
	s_mov_b64 s[4:5], 0x1400000
	v_bfe_u32 v1, v54, 16, 1
	v_lshl_add_u64 v[60:61], v[106:107], 0, s[4:5]
	v_pk_mul_f32 v[56:57], v[56:57], v[66:67] op_sel_hi:[1,0]
	v_add3_u32 v1, v54, v1, s17
	v_bfe_u32 v54, v55, 16, 1
	global_store_dwordx2 v[60:61], v[58:59], off offset:512 sc1
	v_add3_u32 v58, v55, v54, s17
	v_pk_mul_f32 v[54:55], v[16:17], v[56:57]
	v_lshrrev_b32_e32 v1, 16, v1
	v_bfe_u32 v56, v54, 16, 1
	v_add3_u32 v56, v54, v56, s17
	v_bfe_u32 v54, v55, 16, 1
	v_pk_mul_f32 v[50:51], v[50:51], v[66:67] op_sel_hi:[1,0]
	v_add3_u32 v55, v55, v54, s17
	v_and_or_b32 v54, v58, s20, v1
	v_lshrrev_b32_e32 v1, 16, v56
	v_pk_mul_f32 v[50:51], v[10:11], v[50:51]
	v_and_or_b32 v55, v55, s20, v1
	v_bfe_u32 v1, v50, 16, 1
	v_pk_mul_f32 v[52:53], v[52:53], v[66:67] op_sel_hi:[1,0]
	v_add3_u32 v1, v50, v1, s17
	v_bfe_u32 v50, v51, 16, 1
	v_pk_mul_f32 v[52:53], v[12:13], v[52:53]
	v_lshrrev_b32_e32 v1, 16, v1
	v_add3_u32 v50, v51, v50, s17
	v_and_or_b32 v50, v50, s20, v1
	v_bfe_u32 v1, v52, 16, 1
	v_bfe_u32 v51, v53, 16, 1
	v_add3_u32 v1, v52, v1, s17
	v_add3_u32 v51, v53, v51, s17
	s_waitcnt vmcnt(27)
	v_mul_f32_e32 v52, v47, v47
	v_mul_f32_e32 v53, v49, v49
	v_fmac_f32_e32 v52, v46, v46
	v_fmac_f32_e32 v53, v48, v48
	global_store_dwordx2 v[60:61], v[54:55], off offset:1024 sc1
	v_add_f32_e32 v52, v52, v53
	v_mul_f32_e32 v53, v43, v43
	v_mul_f32_e32 v54, v45, v45
	v_fmac_f32_e32 v53, v42, v42
	v_fmac_f32_e32 v54, v44, v44
	v_add_f32_e32 v53, v53, v54
	v_add_f32_e32 v52, v52, v53
	v_mul_f32_e32 v53, v39, v39
	v_mul_f32_e32 v54, v41, v41
	v_fmac_f32_e32 v53, v38, v38
	v_fmac_f32_e32 v54, v40, v40
	v_add_f32_e32 v53, v53, v54
	v_add_f32_e32 v52, v52, v53
	s_waitcnt vmcnt(27)
	v_mul_f32_e32 v53, v35, v35
	v_mul_f32_e32 v54, v37, v37
	v_fmac_f32_e32 v53, v34, v34
	v_fmac_f32_e32 v54, v36, v36
	v_add_f32_e32 v53, v53, v54
	v_add_f32_e32 v52, v52, v53
	s_waitcnt vmcnt(24)
	v_mul_f32_e32 v53, v31, v31
	v_mul_f32_e32 v54, v33, v33
	v_fmac_f32_e32 v53, v30, v30
	v_fmac_f32_e32 v54, v32, v32
	v_add_f32_e32 v53, v53, v54
	v_mul_f32_e32 v54, v27, v27
	v_mul_f32_e32 v55, v29, v29
	v_fmac_f32_e32 v54, v26, v26
	v_fmac_f32_e32 v55, v28, v28
	v_add_f32_e32 v54, v54, v55
	v_add_f32_e32 v53, v53, v54
	v_mul_f32_e32 v54, v23, v23
	v_mul_f32_e32 v55, v25, v25
	v_add_f32_dpp v52, v52, v52 quad_perm:[1,0,3,2] row_mask:0xf bank_mask:0xf bound_ctrl:1
	v_fmac_f32_e32 v54, v22, v22
	v_fmac_f32_e32 v55, v24, v24
	v_add_f32_dpp v52, v52, v52 quad_perm:[2,3,0,1] row_mask:0xf bank_mask:0xf bound_ctrl:1
	v_add_f32_e32 v54, v54, v55
	v_add_f32_e32 v54, v53, v54
	v_add_f32_dpp v52, v52, v52 row_half_mirror row_mask:0xf bank_mask:0xf bound_ctrl:1
	s_waitcnt vmcnt(23)
	v_mul_f32_e32 v53, v19, v19
	v_mul_f32_e32 v55, v21, v21
	v_add_f32_dpp v52, v52, v52 row_ror:8 row_mask:0xf bank_mask:0xf bound_ctrl:1
	v_fmac_f32_e32 v53, v18, v18
	v_fmac_f32_e32 v55, v20, v20
	v_add_f32_e32 v55, v53, v55
	v_mov_b32_e32 v53, v52
	s_nop 1
	v_permlane16_swap_b32_e32 v52, v53
	v_add_f32_e32 v53, v52, v53
	v_add_f32_e32 v52, v54, v55
	v_mov_b32_e32 v55, v53
	s_nop 1
	v_permlane32_swap_b32_e32 v53, v55
	v_add_f32_dpp v52, v52, v52 quad_perm:[1,0,3,2] row_mask:0xf bank_mask:0xf bound_ctrl:1
	v_lshrrev_b32_e32 v1, 16, v1
	v_and_or_b32 v51, v51, s20, v1
	v_add_f32_dpp v52, v52, v52 quad_perm:[2,3,0,1] row_mask:0xf bank_mask:0xf bound_ctrl:1
	global_store_dwordx2 v[60:61], v[50:51], off offset:1536 sc1
	v_lshl_add_u64 v[50:51], v[106:107], 0, s[12:13]
	v_add_f32_dpp v52, v52, v52 row_half_mirror row_mask:0xf bank_mask:0xf bound_ctrl:1
	s_mov_b64 s[4:5], 0x1c00000
	s_nop 0
	v_add_f32_dpp v52, v52, v52 row_ror:8 row_mask:0xf bank_mask:0xf bound_ctrl:1
	v_mov_b32_e32 v54, v52
	s_nop 1
	v_permlane16_swap_b32_e32 v52, v54
	v_add_f32_e32 v52, v52, v54
	v_mov_b32_e32 v54, v52
	s_nop 1
	v_permlane32_swap_b32_e32 v52, v54
	v_pk_add_f32 v[52:53], v[52:53], v[54:55]
	s_nop 0
	v_pk_fma_f32 v[52:53], v[52:53], s[16:17], v[134:135] op_sel_hi:[1,0,0]
	s_nop 0
	v_mul_f32_e32 v54, 0x4b800000, v53
	v_cmp_gt_f32_e32 vcc, s2, v53
	s_nop 1
	v_cndmask_b32_e32 v53, v53, v54, vcc
	v_rsq_f32_e32 v53, v53
	s_nop 0
	v_mul_f32_e32 v1, 0x45800000, v53
	v_cndmask_b32_e32 v54, v53, v1, vcc
	v_pk_mul_f32 v[46:47], v[46:47], v[54:55] op_sel_hi:[1,0]
	v_pk_mul_f32 v[48:49], v[48:49], v[54:55] op_sel_hi:[1,0]
	v_pk_mul_f32 v[46:47], v[2:3], v[46:47]
	v_pk_mul_f32 v[48:49], v[4:5], v[48:49]
	v_bfe_u32 v1, v46, 16, 1
	v_add3_u32 v1, v46, v1, s17
	v_bfe_u32 v46, v47, 16, 1
	v_lshrrev_b32_e32 v1, 16, v1
	v_add3_u32 v46, v47, v46, s17
	v_and_or_b32 v46, v46, s20, v1
	v_bfe_u32 v1, v48, 16, 1
	v_add3_u32 v1, v48, v1, s17
	v_bfe_u32 v47, v49, 16, 1
	v_pk_mul_f32 v[42:43], v[42:43], v[54:55] op_sel_hi:[1,0]
	v_lshrrev_b32_e32 v1, 16, v1
	v_add3_u32 v47, v49, v47, s17
	v_pk_mul_f32 v[42:43], v[6:7], v[42:43]
	v_and_or_b32 v47, v47, s20, v1
	v_bfe_u32 v1, v42, 16, 1
	v_pk_mul_f32 v[44:45], v[44:45], v[54:55] op_sel_hi:[1,0]
	v_add3_u32 v1, v42, v1, s17
	v_bfe_u32 v42, v43, 16, 1
	v_pk_mul_f32 v[44:45], v[8:9], v[44:45]
	v_lshrrev_b32_e32 v1, 16, v1
	v_add3_u32 v42, v43, v42, s17
	v_and_or_b32 v42, v42, s20, v1
	v_bfe_u32 v1, v44, 16, 1
	v_add3_u32 v1, v44, v1, s17
	v_bfe_u32 v43, v45, 16, 1
	v_pk_mul_f32 v[38:39], v[38:39], v[54:55] op_sel_hi:[1,0]
	v_lshrrev_b32_e32 v1, 16, v1
	v_add3_u32 v43, v45, v43, s17
	v_pk_mul_f32 v[38:39], v[14:15], v[38:39]
	v_and_or_b32 v43, v43, s20, v1
	v_bfe_u32 v1, v38, 16, 1
	v_pk_mul_f32 v[40:41], v[40:41], v[54:55] op_sel_hi:[1,0]
	v_add3_u32 v1, v38, v1, s17
	v_bfe_u32 v38, v39, 16, 1
	v_pk_mul_f32 v[40:41], v[16:17], v[40:41]
	v_lshrrev_b32_e32 v1, 16, v1
	v_add3_u32 v38, v39, v38, s17
	v_and_or_b32 v38, v38, s20, v1
	v_bfe_u32 v1, v40, 16, 1
	v_add3_u32 v1, v40, v1, s17
	v_bfe_u32 v39, v41, 16, 1
	v_pk_mul_f32 v[34:35], v[34:35], v[54:55] op_sel_hi:[1,0]
	v_lshrrev_b32_e32 v1, 16, v1
	v_add3_u32 v39, v41, v39, s17
	v_pk_mul_f32 v[34:35], v[10:11], v[34:35]
	v_and_or_b32 v39, v39, s20, v1
	v_bfe_u32 v1, v34, 16, 1
	v_pk_mul_f32 v[36:37], v[36:37], v[54:55] op_sel_hi:[1,0]
	v_add3_u32 v1, v34, v1, s17
	v_bfe_u32 v34, v35, 16, 1
	v_add_co_u32_e32 v48, vcc, s21, v106
	v_pk_mul_f32 v[36:37], v[12:13], v[36:37]
	v_lshrrev_b32_e32 v1, 16, v1
	v_add3_u32 v34, v35, v34, s17
	v_addc_co_u32_e32 v49, vcc, 0, v107, vcc
	v_and_or_b32 v34, v34, s20, v1
	v_bfe_u32 v1, v36, 16, 1
	v_add3_u32 v1, v36, v1, s17
	v_mul_f32_e32 v36, 0x4b800000, v52
	v_cmp_gt_f32_e32 vcc, s2, v52
	v_bfe_u32 v35, v37, 16, 1
	v_lshrrev_b32_e32 v1, 16, v1
	v_cndmask_b32_e32 v36, v52, v36, vcc
	v_rsq_f32_e32 v36, v36
	v_add3_u32 v35, v37, v35, s17
	v_and_or_b32 v35, v35, s20, v1
	global_store_dwordx2 v[48:49], v[46:47], off sc1
	v_mul_f32_e32 v1, 0x45800000, v36
	global_store_dwordx2 v[50:51], v[42:43], off offset:512 sc1
	global_store_dwordx2 v[50:51], v[38:39], off offset:1024 sc1
	global_store_dwordx2 v[50:51], v[34:35], off offset:1536 sc1
	v_cndmask_b32_e32 v34, v36, v1, vcc
	v_pk_mul_f32 v[30:31], v[30:31], v[34:35] op_sel_hi:[1,0]
	v_pk_mul_f32 v[32:33], v[32:33], v[34:35] op_sel_hi:[1,0]
	v_pk_mul_f32 v[2:3], v[2:3], v[30:31]
	v_pk_mul_f32 v[4:5], v[4:5], v[32:33]
	v_bfe_u32 v1, v2, 16, 1
	v_add3_u32 v1, v2, v1, s17
	v_bfe_u32 v2, v3, 16, 1
	v_lshrrev_b32_e32 v1, 16, v1
	v_add3_u32 v2, v3, v2, s17
	v_and_or_b32 v2, v2, s20, v1
	v_bfe_u32 v1, v4, 16, 1
	v_lshl_add_u64 v[36:37], v[106:107], 0, s[4:5]
	v_add3_u32 v1, v4, v1, s17
	v_bfe_u32 v3, v5, 16, 1
	s_mov_b32 s4, 0x1c00000
	v_lshrrev_b32_e32 v1, 16, v1
	v_add3_u32 v3, v5, v3, s17
	v_add_co_u32_e32 v4, vcc, s4, v106
	v_and_or_b32 v3, v3, s20, v1
	s_nop 0
	v_addc_co_u32_e32 v5, vcc, 0, v107, vcc
	global_store_dwordx2 v[4:5], v[2:3], off sc1
	v_pk_mul_f32 v[2:3], v[26:27], v[34:35] op_sel_hi:[1,0]
	v_pk_mul_f32 v[4:5], v[28:29], v[34:35] op_sel_hi:[1,0]
	v_pk_mul_f32 v[2:3], v[6:7], v[2:3]
	v_pk_mul_f32 v[4:5], v[8:9], v[4:5]
	v_bfe_u32 v1, v2, 16, 1
	v_add3_u32 v1, v2, v1, s17
	v_bfe_u32 v2, v3, 16, 1
	v_lshrrev_b32_e32 v1, 16, v1
	v_add3_u32 v2, v3, v2, s17
	v_and_or_b32 v2, v2, s20, v1
	v_bfe_u32 v1, v4, 16, 1
	v_add3_u32 v1, v4, v1, s17
	v_bfe_u32 v3, v5, 16, 1
	v_lshrrev_b32_e32 v1, 16, v1
	v_add3_u32 v3, v5, v3, s17
	v_and_or_b32 v3, v3, s20, v1
	global_store_dwordx2 v[36:37], v[2:3], off offset:512 sc1
	v_pk_mul_f32 v[2:3], v[22:23], v[34:35] op_sel_hi:[1,0]
	v_pk_mul_f32 v[4:5], v[24:25], v[34:35] op_sel_hi:[1,0]
	v_pk_mul_f32 v[2:3], v[14:15], v[2:3]
	v_pk_mul_f32 v[4:5], v[16:17], v[4:5]
	v_bfe_u32 v1, v2, 16, 1
	v_add3_u32 v1, v2, v1, s17
	v_bfe_u32 v2, v3, 16, 1
	v_lshrrev_b32_e32 v1, 16, v1
	v_add3_u32 v2, v3, v2, s17
	v_and_or_b32 v2, v2, s20, v1
	v_bfe_u32 v1, v4, 16, 1
	v_add3_u32 v1, v4, v1, s17
	v_bfe_u32 v3, v5, 16, 1
	v_lshrrev_b32_e32 v1, 16, v1
	v_add3_u32 v3, v5, v3, s17
	v_and_or_b32 v3, v3, s20, v1
	global_store_dwordx2 v[36:37], v[2:3], off offset:1024 sc1
	v_pk_mul_f32 v[2:3], v[18:19], v[34:35] op_sel_hi:[1,0]
	v_pk_mul_f32 v[4:5], v[20:21], v[34:35] op_sel_hi:[1,0]
	v_pk_mul_f32 v[2:3], v[10:11], v[2:3]
	v_pk_mul_f32 v[4:5], v[12:13], v[4:5]
	v_bfe_u32 v1, v2, 16, 1
	v_add3_u32 v1, v2, v1, s17
	v_bfe_u32 v2, v3, 16, 1
	v_lshrrev_b32_e32 v1, 16, v1
	v_add3_u32 v2, v3, v2, s17
	v_and_or_b32 v2, v2, s20, v1
	v_bfe_u32 v1, v4, 16, 1
	v_add3_u32 v1, v4, v1, s17
	v_bfe_u32 v3, v5, 16, 1
	v_lshrrev_b32_e32 v1, 16, v1
	v_add3_u32 v3, v5, v3, s17
	v_and_or_b32 v3, v3, s20, v1
	global_store_dwordx2 v[36:37], v[2:3], off offset:1536 sc1
	s_cbranch_scc1 .LBB0_69
	s_lshl_b64 s[4:5], s[62:63], 10
	s_lshl_b64 s[4:5], s[4:5], 2
	s_add_u32 s4, s42, s4
	s_addc_u32 s5, s43, s5
	global_load_dwordx4 v[2:5], v130, s[4:5] nt
	global_load_dwordx4 v[6:9], v130, s[4:5] offset:1024 nt
	global_load_dwordx4 v[10:13], v130, s[4:5] offset:2048 nt
	global_load_dwordx4 v[14:17], v130, s[4:5] offset:3072 nt
	v_lshl_add_u64 v[30:31], s[54:55], 0, v[130:131]
	global_load_dwordx4 v[18:21], v[30:31], off
	global_load_dwordx4 v[22:25], v[30:31], off offset:1024
	global_load_dwordx4 v[26:29], v[30:31], off offset:2048
	v_mov_b32_e32 v1, 0x358637bd
	global_load_dwordx4 v[30:33], v[30:31], off offset:3072
	s_add_u32 s4, s6, s10
	s_addc_u32 s5, s7, s11
	v_lshl_add_u64 v[34:35], s[4:5], 0, v[132:133]
	v_lshl_add_u64 v[36:37], v[34:35], 0, s[8:9]
	v_add_co_u32_e64 v34, s[6:7], s3, v34
	s_waitcnt vmcnt(7)
	v_mul_f32_e32 v38, v3, v3
	v_mul_f32_e32 v39, v5, v5
	s_waitcnt vmcnt(6)
	v_mul_f32_e32 v40, v7, v7
	v_mul_f32_e32 v41, v9, v9
	s_waitcnt vmcnt(5)
	v_mul_f32_e32 v42, v11, v11
	v_mul_f32_e32 v43, v13, v13
	v_fmac_f32_e32 v38, v2, v2
	v_fmac_f32_e32 v39, v4, v4
	v_fmac_f32_e32 v40, v6, v6
	v_fmac_f32_e32 v41, v8, v8
	s_waitcnt vmcnt(4)
	v_mul_f32_e32 v44, v15, v15
	v_mul_f32_e32 v45, v17, v17
	v_fmac_f32_e32 v42, v10, v10
	v_fmac_f32_e32 v43, v12, v12
	v_add_f32_e32 v38, v38, v39
	v_add_f32_e32 v39, v40, v41
	v_fmac_f32_e32 v44, v14, v14
	v_fmac_f32_e32 v45, v16, v16
	v_add_f32_e32 v40, v42, v43
	v_add_f32_e32 v38, v38, v39
	v_add_f32_e32 v41, v44, v45
	v_add_f32_e32 v38, v38, v40
	v_add_f32_e32 v38, v38, v41
	v_addc_co_u32_e64 v35, s[6:7], 0, v35, s[6:7]
	s_nop 0
	v_add_f32_dpp v38, v38, v38 quad_perm:[1,0,3,2] row_mask:0xf bank_mask:0xf bound_ctrl:1
	s_nop 1
	v_add_f32_dpp v38, v38, v38 quad_perm:[2,3,0,1] row_mask:0xf bank_mask:0xf bound_ctrl:1
	s_nop 1
	v_add_f32_dpp v38, v38, v38 row_half_mirror row_mask:0xf bank_mask:0xf bound_ctrl:1
	s_nop 1
	v_add_f32_dpp v38, v38, v38 row_ror:8 row_mask:0xf bank_mask:0xf bound_ctrl:1
	v_mov_b32_e32 v39, v38
	s_nop 1
	v_permlane16_swap_b32_e32 v38, v39
	v_add_f32_e32 v38, v38, v39
	v_mov_b32_e32 v39, v38
	s_nop 1
	v_permlane32_swap_b32_e32 v38, v39
	v_add_f32_e32 v38, v38, v39
	v_fmac_f32_e32 v1, 0x3a800000, v38
	v_mul_f32_e32 v38, 0x4b800000, v1
	v_cmp_gt_f32_e32 vcc, s2, v1
	s_nop 1
	v_cndmask_b32_e32 v1, v1, v38, vcc
	v_rsq_f32_e32 v1, v1
	s_nop 0
	v_mul_f32_e32 v38, 0x45800000, v1
	v_cndmask_b32_e32 v38, v1, v38, vcc
	v_pk_mul_f32 v[2:3], v[2:3], v[38:39] op_sel_hi:[1,0]
	v_pk_mul_f32 v[4:5], v[4:5], v[38:39] op_sel_hi:[1,0]
	v_pk_mul_f32 v[6:7], v[6:7], v[38:39] op_sel_hi:[1,0]
	v_pk_mul_f32 v[8:9], v[8:9], v[38:39] op_sel_hi:[1,0]
	v_pk_mul_f32 v[10:11], v[10:11], v[38:39] op_sel_hi:[1,0]
	v_pk_mul_f32 v[12:13], v[12:13], v[38:39] op_sel_hi:[1,0]
	s_waitcnt vmcnt(3)
	v_pk_mul_f32 v[4:5], v[20:21], v[4:5]
	v_pk_mul_f32 v[2:3], v[18:19], v[2:3]
	s_waitcnt vmcnt(2)
	v_pk_mul_f32 v[8:9], v[24:25], v[8:9]
	v_pk_mul_f32 v[6:7], v[22:23], v[6:7]
	s_waitcnt vmcnt(1)
	v_pk_mul_f32 v[12:13], v[28:29], v[12:13]
	v_pk_mul_f32 v[10:11], v[26:27], v[10:11]
	v_bfe_u32 v1, v2, 16, 1
	v_bfe_u32 v18, v3, 16, 1
	v_bfe_u32 v19, v4, 16, 1
	v_bfe_u32 v20, v5, 16, 1
	v_bfe_u32 v21, v6, 16, 1
	v_bfe_u32 v22, v7, 16, 1
	v_bfe_u32 v23, v8, 16, 1
	v_bfe_u32 v24, v9, 16, 1
	v_bfe_u32 v25, v10, 16, 1
	v_bfe_u32 v26, v11, 16, 1
	v_bfe_u32 v27, v12, 16, 1
	v_add3_u32 v1, v2, v1, s17
	v_add3_u32 v2, v3, v18, s17
	v_add3_u32 v3, v4, v19, s17
	v_add3_u32 v4, v5, v20, s17
	v_add3_u32 v5, v6, v21, s17
	v_add3_u32 v6, v7, v22, s17
	v_add3_u32 v7, v8, v23, s17
	v_bfe_u32 v28, v13, 16, 1
	v_add3_u32 v8, v9, v24, s17
	v_add3_u32 v9, v10, v25, s17
	v_add3_u32 v10, v11, v26, s17
	v_add3_u32 v11, v12, v27, s17
	v_lshrrev_b32_e32 v1, 16, v1
	v_lshrrev_b32_e32 v3, 16, v3
	v_lshrrev_b32_e32 v5, 16, v5
	v_lshrrev_b32_e32 v7, 16, v7
	v_pk_mul_f32 v[14:15], v[14:15], v[38:39] op_sel_hi:[1,0]
	v_add3_u32 v12, v13, v28, s17
	v_lshrrev_b32_e32 v9, 16, v9
	v_lshrrev_b32_e32 v11, 16, v11
	v_and_or_b32 v2, v2, s20, v1
	v_and_or_b32 v3, v4, s20, v3
	v_and_or_b32 v4, v6, s20, v5
	v_and_or_b32 v5, v8, s20, v7
	v_and_or_b32 v6, v10, s20, v9
	v_and_or_b32 v7, v12, s20, v11
	global_store_dwordx2 v[34:35], v[2:3], off sc1
	global_store_dwordx2 v[36:37], v[4:5], off offset:512 sc1
	global_store_dwordx2 v[36:37], v[6:7], off offset:1024 sc1
	s_waitcnt vmcnt(3)
	v_pk_mul_f32 v[4:5], v[30:31], v[14:15]
	v_pk_mul_f32 v[2:3], v[16:17], v[38:39] op_sel_hi:[1,0]
	v_bfe_u32 v1, v4, 16, 1
	v_add3_u32 v1, v4, v1, s17
	v_bfe_u32 v4, v5, 16, 1
	v_pk_mul_f32 v[2:3], v[32:33], v[2:3]
	v_lshrrev_b32_e32 v1, 16, v1
	v_add3_u32 v4, v5, v4, s17
	v_and_or_b32 v4, v4, s20, v1
	v_bfe_u32 v1, v2, 16, 1
	v_add3_u32 v1, v2, v1, s17
	v_bfe_u32 v2, v3, 16, 1
	v_lshrrev_b32_e32 v1, 16, v1
	v_add3_u32 v2, v3, v2, s17
	v_and_or_b32 v5, v2, s20, v1
	global_store_dwordx2 v[36:37], v[4:5], off offset:1536 sc1
